# attention softmax row-sum tree: packed adds/movs split into scalar pairs (on top of the rescale split)
# baseline (speedup 1.0000x reference)
; #define PV_STEP(OACC, mm, ktt, ss, PF) do { OACC = __builtin_amdgcn_mfma_f32_32x32x16_bf16(ldA_perm(vb + (mm) * 32 * 72 + 32 * (ktt) + 16 * (ss)), PF, OACC, 0, 0, 0); } while (0)
; __device__ __forceinline__ void attn_phase(const Ctx& c, const Params& p, int o, int first, int cidx) {
;     ...
;                 f32x16 e0, e1;
; #pragma unroll
;                 for (int r = 0; r < 16; ++r) { e0[r] = __builtin_amdgcn_exp2f(p0[r] - mnew); e1[r] = __builtin_amdgcn_exp2f(p1[r] - mnew); }
;                 p0 = e0; p1 = e1;
;                 { const f32x16 t = e0 + e1; lrun += ((t[0] + t[1]) + (t[2] + t[3])) + ((t[4] + t[5]) + (t[6] + t[7])) + ((t[8] + t[9]) + (t[10] + t[11])) + ((t[12] + t[13]) + (t[14] + t[15])); }
;                 const bf16x8 pf00 = pkfrag(p0, 0), pf01 = pkfrag(p0, 1), pf10 = pkfrag(p1, 0), pf11 = pkfrag(p1, 1);
;     ...
;                 PV_STEP(o0, 0, 0, 0, pf00); PV_STEP(o0, 0, 0, 1, pf01); PV_STEP(o0, 0, 1, 0, pf10); PV_STEP(o0, 0, 1, 1, pf11);
;                 PV_STEP(o1, 1, 0, 0, pf00); PV_STEP(o1, 1, 0, 1, pf01); PV_STEP(o1, 1, 1, 0, pf10); PV_STEP(o1, 1, 1, 1, pf11);
.LBB0_129:
	v_sub_f32_e32 v38, v38, v1
	v_exp_f32_e32 v138, v38
	v_sub_f32_e32 v38, v55, v1
	v_exp_f32_e32 v55, v38
	v_sub_f32_e32 v38, v39, v1
	v_sub_f32_e32 v39, v40, v1
	v_sub_f32_e32 v40, v41, v1
	v_sub_f32_e32 v41, v42, v1
	v_sub_f32_e32 v42, v43, v1
	v_exp_f32_e32 v139, v38
	v_sub_f32_e32 v38, v56, v1
	v_exp_f32_e32 v56, v39
	v_sub_f32_e32 v39, v57, v1
	v_exp_f32_e32 v57, v40
	v_sub_f32_e32 v40, v58, v1
	v_exp_f32_e32 v58, v41
	v_sub_f32_e32 v41, v59, v1
	v_exp_f32_e32 v59, v42
	v_sub_f32_e32 v42, v60, v1
	v_exp_f32_e32 v60, v42
	v_sub_f32_e32 v42, v44, v1
	v_exp_f32_e32 v140, v42
	v_sub_f32_e32 v42, v61, v1
	v_exp_f32_e32 v61, v42
	v_sub_f32_e32 v42, v45, v1
	v_exp_f32_e32 v141, v42
	v_sub_f32_e32 v42, v62, v1
	v_exp_f32_e32 v44, v42
	v_sub_f32_e32 v42, v46, v1
	v_exp_f32_e32 v62, v42
	v_sub_f32_e32 v42, v63, v1
	v_sub_f32_e32 v50, v50, v1
	v_sub_f32_e32 v34, v34, v1
	v_sub_f32_e32 v51, v51, v1
	v_sub_f32_e32 v35, v35, v1
	v_sub_f32_e32 v52, v52, v1
	v_sub_f32_e32 v36, v36, v1
	v_sub_f32_e32 v53, v53, v1
	v_sub_f32_e32 v37, v37, v1
	v_exp_f32_e32 v45, v42
	v_sub_f32_e32 v42, v47, v1
	v_exp_f32_e32 v50, v50
	v_exp_f32_e32 v34, v34
	v_exp_f32_e32 v51, v51
	v_exp_f32_e32 v35, v35
	v_exp_f32_e32 v52, v52
	v_exp_f32_e32 v36, v36
	v_exp_f32_e32 v53, v53
	v_exp_f32_e32 v37, v37
	v_sub_f32_e32 v54, v54, v1
	v_exp_f32_e32 v63, v42
	v_sub_f32_e32 v42, v64, v1
	v_exp_f32_e32 v54, v54
	v_exp_f32_e32 v38, v38
	v_exp_f32_e32 v39, v39
	v_exp_f32_e32 v64, v42
	v_sub_f32_e32 v42, v48, v1
	v_exp_f32_e32 v142, v42
	v_sub_f32_e32 v42, v65, v1
	v_exp_f32_e32 v65, v42
	v_sub_f32_e32 v42, v49, v1
	v_exp_f32_e32 v40, v40
	v_exp_f32_e32 v41, v41
	v_exp_f32_e32 v143, v42
	v_add_f32_e32 v184, v52, v36
	v_add_f32_e32 v185, v53, v37
	v_add_f32_e32 v186, v50, v34
	v_add_f32_e32 v187, v51, v35
	v_add_f32_e32 v170, v38, v56
	v_add_f32_e32 v171, v39, v57
	v_add_f32_e32 v174, v54, v138
	v_add_f32_e32 v175, v55, v139
	v_mov_b32_e32 v188, v187
	v_mov_b32_e32 v189, v184
	v_mov_b32_e32 v187, v185
	v_add_f32_e32 v184, v188, v186
	v_add_f32_e32 v185, v189, v187
	v_mov_b32_e32 v186, v175
	v_mov_b32_e32 v187, v170
	v_mov_b32_e32 v175, v171
	v_add_f32_e32 v170, v186, v174
	v_add_f32_e32 v171, v187, v175
	v_add_f32_e32 v42, v64, v142
	v_add_f32_e32 v43, v65, v143
	v_add_f32_e32 v46, v44, v62
	v_add_f32_e32 v47, v45, v63
	v_add_f32_e32 v48, v60, v140
	v_add_f32_e32 v49, v61, v141
	v_add_f32_e32 v168, v40, v58
	v_add_f32_e32 v169, v41, v59
	v_add_f32_e32 v185, v184, v185
	v_add_f32_e32 v184, v184, v184
	v_add_f32_e32 v171, v170, v171
	v_add_f32_e32 v170, v170, v170
	v_add_f32_e32 v169, v168, v169
	v_add_f32_e32 v49, v48, v49
	v_mov_b32_e32 v168, v46
	v_mov_b32_e32 v48, v47
	v_mov_b32_e32 v184, v42
	v_mov_b32_e32 v170, v43
	s_mul_i32 s10, s18, 0x2400
	v_add_f32_e32 v46, v168, v48
	v_add_f32_e32 v47, v169, v49
	v_add_f32_e32 v42, v184, v170
	v_add_f32_e32 v43, v185, v171
	v_cvt_pk_bf16_f32 v49, v38, v39
	v_add_f32_e32 v42, v46, v42
	v_add_f32_e32 v43, v47, v43
	v_cvt_pk_bf16_f32 v38, v34, v35
	v_cvt_pk_bf16_f32 v34, v58, v59
	v_add_u32_e32 v58, s10, v131
	v_add_f32_e32 v42, v42, v43
	v_add_u32_e32 v59, 0x6800, v58
	v_add_f32_e32 v136, v42, v136
	v_cvt_pk_bf16_f32 v46, v50, v51
	v_cvt_pk_bf16_f32 v47, v52, v53
	v_cvt_pk_bf16_f32 v48, v54, v55
	v_cvt_pk_bf16_f32 v42, v40, v41
	v_cvt_pk_bf16_f32 v41, v56, v57
	s_waitcnt lgkmcnt(0)
	v_mfma_f32_32x32x16_bf16 v[18:33], v[200:203], v[46:49], v[18:33]
	v_cvt_pk_bf16_f32 v43, v60, v61
	v_cvt_pk_bf16_f32 v44, v44, v45
	v_cvt_pk_bf16_f32 v45, v64, v65
	v_cvt_pk_bf16_f32 v39, v36, v37
	v_cvt_pk_bf16_f32 v40, v138, v139
	v_cvt_pk_bf16_f32 v35, v140, v141
	v_cvt_pk_bf16_f32 v36, v62, v63
	v_cvt_pk_bf16_f32 v37, v142, v143
	v_mfma_f32_32x32x16_bf16 v[2:17], v[216:219], v[46:49], v[2:17]
	v_mfma_f32_32x32x16_bf16 v[18:33], v[204:207], v[42:45], v[18:33]
	v_mfma_f32_32x32x16_bf16 v[2:17], v[220:223], v[42:45], v[2:17]
	v_mfma_f32_32x32x16_bf16 v[18:33], v[208:211], v[38:41], v[18:33]
	v_mfma_f32_32x32x16_bf16 v[2:17], v[224:227], v[38:41], v[2:17]
	v_mfma_f32_32x32x16_bf16 v[18:33], v[212:215], v[34:37], v[18:33]
	v_mfma_f32_32x32x16_bf16 v[2:17], v[228:231], v[34:37], v[2:17]
	s_andn2_b64 vcc, exec, s[2:3]
	s_cbranch_vccz .LBB0_131
	s_branch .LBB0_134

; #define PV_STEP(OACC, mm, ktt, ss, PF) do { OACC = __builtin_amdgcn_mfma_f32_32x32x16_bf16(ldA_perm(vb + (mm) * 32 * 72 + 32 * (ktt) + 16 * (ss)), PF, OACC, 0, 0, 0); } while (0)
; __device__ __forceinline__ void attn_phase(const Ctx& c, const Params& p, int o, int first, int cidx) {
;     ...
;                 f32x16 e0, e1;
; #pragma unroll
;                 for (int r = 0; r < 16; ++r) { e0[r] = __builtin_amdgcn_exp2f(p0[r] - mnew); e1[r] = __builtin_amdgcn_exp2f(p1[r] - mnew); }
;                 p0 = e0; p1 = e1;
;                 { const f32x16 t = e0 + e1; lrun += ((t[0] + t[1]) + (t[2] + t[3])) + ((t[4] + t[5]) + (t[6] + t[7])) + ((t[8] + t[9]) + (t[10] + t[11])) + ((t[12] + t[13]) + (t[14] + t[15])); }
;                 const bf16x8 pf00 = pkfrag(p0, 0), pf01 = pkfrag(p0, 1), pf10 = pkfrag(p1, 0), pf11 = pkfrag(p1, 1);
;     ...
;                 PV_STEP(o0, 0, 0, 0, pf00); PV_STEP(o0, 0, 0, 1, pf01); PV_STEP(o0, 0, 1, 0, pf10); PV_STEP(o0, 0, 1, 1, pf11);
;                 PV_STEP(o1, 1, 0, 0, pf00); PV_STEP(o1, 1, 0, 1, pf01); PV_STEP(o1, 1, 1, 0, pf10); PV_STEP(o1, 1, 1, 1, pf11);
.Lsb_129:
	v_sub_f32_e32 v38, v38, v1
	v_exp_f32_e32 v138, v38
	v_sub_f32_e32 v38, v55, v1
	v_exp_f32_e32 v55, v38
	v_sub_f32_e32 v38, v39, v1
	v_sub_f32_e32 v39, v40, v1
	v_sub_f32_e32 v40, v41, v1
	v_sub_f32_e32 v41, v42, v1
	v_sub_f32_e32 v42, v43, v1
	v_exp_f32_e32 v139, v38
	v_sub_f32_e32 v38, v56, v1
	v_exp_f32_e32 v56, v39
	v_sub_f32_e32 v39, v57, v1
	v_exp_f32_e32 v57, v40
	v_sub_f32_e32 v40, v58, v1
	v_exp_f32_e32 v58, v41
	v_sub_f32_e32 v41, v59, v1
	v_exp_f32_e32 v59, v42
	v_sub_f32_e32 v42, v60, v1
	v_exp_f32_e32 v60, v42
	v_sub_f32_e32 v42, v44, v1
	v_exp_f32_e32 v140, v42
	v_sub_f32_e32 v42, v61, v1
	v_exp_f32_e32 v61, v42
	v_sub_f32_e32 v42, v45, v1
	v_exp_f32_e32 v141, v42
	v_sub_f32_e32 v42, v62, v1
	v_exp_f32_e32 v44, v42
	v_sub_f32_e32 v42, v46, v1
	v_exp_f32_e32 v62, v42
	v_sub_f32_e32 v42, v63, v1
	v_sub_f32_e32 v50, v50, v1
	v_sub_f32_e32 v34, v34, v1
	v_sub_f32_e32 v51, v51, v1
	v_sub_f32_e32 v35, v35, v1
	v_sub_f32_e32 v52, v52, v1
	v_sub_f32_e32 v36, v36, v1
	v_sub_f32_e32 v53, v53, v1
	v_sub_f32_e32 v37, v37, v1
	v_exp_f32_e32 v45, v42
	v_sub_f32_e32 v42, v47, v1
	v_exp_f32_e32 v50, v50
	v_exp_f32_e32 v34, v34
	v_exp_f32_e32 v51, v51
	v_exp_f32_e32 v35, v35
	v_exp_f32_e32 v52, v52
	v_exp_f32_e32 v36, v36
	v_exp_f32_e32 v53, v53
	v_exp_f32_e32 v37, v37
	v_sub_f32_e32 v54, v54, v1
	v_exp_f32_e32 v63, v42
	v_sub_f32_e32 v42, v64, v1
	v_exp_f32_e32 v54, v54
	v_exp_f32_e32 v38, v38
	v_exp_f32_e32 v39, v39
	v_exp_f32_e32 v64, v42
	v_sub_f32_e32 v42, v48, v1
	v_exp_f32_e32 v142, v42
	v_sub_f32_e32 v42, v65, v1
	v_exp_f32_e32 v65, v42
	v_sub_f32_e32 v42, v49, v1
	v_exp_f32_e32 v40, v40
	v_exp_f32_e32 v41, v41
	v_exp_f32_e32 v143, v42
	v_add_f32_e32 v184, v52, v36
	v_add_f32_e32 v185, v53, v37
	v_add_f32_e32 v186, v50, v34
	v_add_f32_e32 v187, v51, v35
	v_add_f32_e32 v170, v38, v56
	v_add_f32_e32 v171, v39, v57
	v_add_f32_e32 v174, v54, v138
	v_add_f32_e32 v175, v55, v139
	v_mov_b32_e32 v188, v187
	v_mov_b32_e32 v189, v184
	v_mov_b32_e32 v187, v185
	v_add_f32_e32 v184, v188, v186
	v_add_f32_e32 v185, v189, v187
	v_mov_b32_e32 v186, v175
	v_mov_b32_e32 v187, v170
	v_mov_b32_e32 v175, v171
	v_add_f32_e32 v170, v186, v174
	v_add_f32_e32 v171, v187, v175
	v_add_f32_e32 v42, v64, v142
	v_add_f32_e32 v43, v65, v143
	v_add_f32_e32 v46, v44, v62
	v_add_f32_e32 v47, v45, v63
	v_add_f32_e32 v48, v60, v140
	v_add_f32_e32 v49, v61, v141
	v_add_f32_e32 v168, v40, v58
	v_add_f32_e32 v169, v41, v59
	v_add_f32_e32 v185, v184, v185
	v_add_f32_e32 v184, v184, v184
	v_add_f32_e32 v171, v170, v171
	v_add_f32_e32 v170, v170, v170
	v_add_f32_e32 v169, v168, v169
	v_add_f32_e32 v49, v48, v49
	v_mov_b32_e32 v168, v46
	v_mov_b32_e32 v48, v47
	v_mov_b32_e32 v184, v42
	v_mov_b32_e32 v170, v43
	s_mul_i32 s10, s18, 0x2400
	v_add_f32_e32 v46, v168, v48
	v_add_f32_e32 v47, v169, v49
	v_add_f32_e32 v42, v184, v170
	v_add_f32_e32 v43, v185, v171
	v_cvt_pk_bf16_f32 v49, v38, v39
	v_add_f32_e32 v42, v46, v42
	v_add_f32_e32 v43, v47, v43
	v_cvt_pk_bf16_f32 v38, v34, v35
	v_cvt_pk_bf16_f32 v34, v58, v59
	v_add_u32_e32 v58, s10, v131
	v_add_f32_e32 v42, v42, v43
	v_add_u32_e32 v59, 0x6800, v58
	v_add_f32_e32 v136, v42, v136
	v_cvt_pk_bf16_f32 v46, v50, v51
	v_cvt_pk_bf16_f32 v47, v52, v53
	v_cvt_pk_bf16_f32 v48, v54, v55
	v_cvt_pk_bf16_f32 v42, v40, v41
	v_cvt_pk_bf16_f32 v41, v56, v57
	s_waitcnt lgkmcnt(0)
	v_mfma_f32_32x32x16_bf16 v[18:33], v[200:203], v[46:49], v[18:33]
	v_cvt_pk_bf16_f32 v43, v60, v61
	v_cvt_pk_bf16_f32 v44, v44, v45
	v_cvt_pk_bf16_f32 v45, v64, v65
	v_cvt_pk_bf16_f32 v39, v36, v37
	v_cvt_pk_bf16_f32 v40, v138, v139
	v_cvt_pk_bf16_f32 v35, v140, v141
	v_cvt_pk_bf16_f32 v36, v62, v63
	v_cvt_pk_bf16_f32 v37, v142, v143
	v_mfma_f32_32x32x16_bf16 v[2:17], v[216:219], v[46:49], v[2:17]
	v_mfma_f32_32x32x16_bf16 v[18:33], v[204:207], v[42:45], v[18:33]
	v_mfma_f32_32x32x16_bf16 v[2:17], v[220:223], v[42:45], v[2:17]
	v_mfma_f32_32x32x16_bf16 v[18:33], v[208:211], v[38:41], v[18:33]
	v_mfma_f32_32x32x16_bf16 v[2:17], v[224:227], v[38:41], v[2:17]
	v_mfma_f32_32x32x16_bf16 v[18:33], v[212:215], v[34:37], v[18:33]
	v_mfma_f32_32x32x16_bf16 v[2:17], v[228:231], v[34:37], v[2:17]
	v_mov_b32_e32 v137, v1

; #define PV_STEP(OACC, mm, ktt, ss, PF) do { OACC = __builtin_amdgcn_mfma_f32_32x32x16_bf16(ldA_perm(vb + (mm) * 32 * 72 + 32 * (ktt) + 16 * (ss)), PF, OACC, 0, 0, 0); } while (0)
; __device__ __forceinline__ void attn_phase(const Ctx& c, const Params& p, int o, int first, int cidx) {
;     ...
;                 f32x16 e0, e1;
; #pragma unroll
;                 for (int r = 0; r < 16; ++r) { e0[r] = __builtin_amdgcn_exp2f(p0[r] - mnew); e1[r] = __builtin_amdgcn_exp2f(p1[r] - mnew); }
;                 p0 = e0; p1 = e1;
;                 { const f32x16 t = e0 + e1; lrun += ((t[0] + t[1]) + (t[2] + t[3])) + ((t[4] + t[5]) + (t[6] + t[7])) + ((t[8] + t[9]) + (t[10] + t[11])) + ((t[12] + t[13]) + (t[14] + t[15])); }
;                 const bf16x8 pf00 = pkfrag(p0, 0), pf01 = pkfrag(p0, 1), pf10 = pkfrag(p1, 0), pf11 = pkfrag(p1, 1);
;     ...
;                 PV_STEP(o0, 0, 0, 0, pf00); PV_STEP(o0, 0, 0, 1, pf01); PV_STEP(o0, 0, 1, 0, pf10); PV_STEP(o0, 0, 1, 1, pf11);
;                 PV_STEP(o1, 1, 0, 0, pf00); PV_STEP(o1, 1, 0, 1, pf01); PV_STEP(o1, 1, 1, 0, pf10); PV_STEP(o1, 1, 1, 1, pf11);
.Lsb_129b:
	v_sub_f32_e32 v38, v38, v1
	v_exp_f32_e32 v138, v38
	v_sub_f32_e32 v38, v55, v1
	v_exp_f32_e32 v55, v38
	v_sub_f32_e32 v38, v39, v1
	v_sub_f32_e32 v39, v40, v1
	v_sub_f32_e32 v40, v41, v1
	v_sub_f32_e32 v41, v42, v1
	v_sub_f32_e32 v42, v43, v1
	v_exp_f32_e32 v139, v38
	v_sub_f32_e32 v38, v56, v1
	v_exp_f32_e32 v56, v39
	v_sub_f32_e32 v39, v57, v1
	v_exp_f32_e32 v57, v40
	v_sub_f32_e32 v40, v58, v1
	v_exp_f32_e32 v58, v41
	v_sub_f32_e32 v41, v59, v1
	v_exp_f32_e32 v59, v42
	v_sub_f32_e32 v42, v60, v1
	v_exp_f32_e32 v60, v42
	v_sub_f32_e32 v42, v44, v1
	v_exp_f32_e32 v140, v42
	v_sub_f32_e32 v42, v61, v1
	v_exp_f32_e32 v61, v42
	v_sub_f32_e32 v42, v45, v1
	v_exp_f32_e32 v141, v42
	v_sub_f32_e32 v42, v62, v1
	v_exp_f32_e32 v44, v42
	v_sub_f32_e32 v42, v46, v1
	v_exp_f32_e32 v62, v42
	v_sub_f32_e32 v42, v63, v1
	v_sub_f32_e32 v50, v50, v1
	v_sub_f32_e32 v34, v34, v1
	v_sub_f32_e32 v51, v51, v1
	v_sub_f32_e32 v35, v35, v1
	v_sub_f32_e32 v52, v52, v1
	v_sub_f32_e32 v36, v36, v1
	v_sub_f32_e32 v53, v53, v1
	v_sub_f32_e32 v37, v37, v1
	v_exp_f32_e32 v45, v42
	v_sub_f32_e32 v42, v47, v1
	v_exp_f32_e32 v50, v50
	v_exp_f32_e32 v34, v34
	v_exp_f32_e32 v51, v51
	v_exp_f32_e32 v35, v35
	v_exp_f32_e32 v52, v52
	v_exp_f32_e32 v36, v36
	v_exp_f32_e32 v53, v53
	v_exp_f32_e32 v37, v37
	v_sub_f32_e32 v54, v54, v1
	v_exp_f32_e32 v63, v42
	v_sub_f32_e32 v42, v64, v1
	v_exp_f32_e32 v54, v54
	v_exp_f32_e32 v38, v38
	v_exp_f32_e32 v39, v39
	v_exp_f32_e32 v64, v42
	v_sub_f32_e32 v42, v48, v1
	v_exp_f32_e32 v142, v42
	v_sub_f32_e32 v42, v65, v1
	v_exp_f32_e32 v65, v42
	v_sub_f32_e32 v42, v49, v1
	v_exp_f32_e32 v40, v40
	v_exp_f32_e32 v41, v41
	v_exp_f32_e32 v143, v42
	v_add_f32_e32 v184, v52, v36
	v_add_f32_e32 v185, v53, v37
	v_add_f32_e32 v186, v50, v34
	v_add_f32_e32 v187, v51, v35
	v_add_f32_e32 v170, v38, v56
	v_add_f32_e32 v171, v39, v57
	v_add_f32_e32 v174, v54, v138
	v_add_f32_e32 v175, v55, v139
	v_mov_b32_e32 v188, v187
	v_mov_b32_e32 v189, v184
	v_mov_b32_e32 v187, v185
	v_add_f32_e32 v184, v188, v186
	v_add_f32_e32 v185, v189, v187
	v_mov_b32_e32 v186, v175
	v_mov_b32_e32 v187, v170
	v_mov_b32_e32 v175, v171
	v_add_f32_e32 v170, v186, v174
	v_add_f32_e32 v171, v187, v175
	v_add_f32_e32 v42, v64, v142
	v_add_f32_e32 v43, v65, v143
	v_add_f32_e32 v46, v44, v62
	v_add_f32_e32 v47, v45, v63
	v_add_f32_e32 v48, v60, v140
	v_add_f32_e32 v49, v61, v141
	v_add_f32_e32 v168, v40, v58
	v_add_f32_e32 v169, v41, v59
	v_add_f32_e32 v185, v184, v185
	v_add_f32_e32 v184, v184, v184
	v_add_f32_e32 v171, v170, v171
	v_add_f32_e32 v170, v170, v170
	v_add_f32_e32 v169, v168, v169
	v_add_f32_e32 v49, v48, v49
	v_mov_b32_e32 v168, v46
	v_mov_b32_e32 v48, v47
	v_mov_b32_e32 v184, v42
	v_mov_b32_e32 v170, v43
	s_mul_i32 s10, s18, 0x2400
	v_add_f32_e32 v46, v168, v48
	v_add_f32_e32 v47, v169, v49
	v_add_f32_e32 v42, v184, v170
	v_add_f32_e32 v43, v185, v171
	v_cvt_pk_bf16_f32 v49, v38, v39
	v_add_f32_e32 v42, v46, v42
	v_add_f32_e32 v43, v47, v43
	v_cvt_pk_bf16_f32 v38, v34, v35
	v_cvt_pk_bf16_f32 v34, v58, v59
	v_add_u32_e32 v58, s10, v131
	v_add_f32_e32 v42, v42, v43
	v_add_u32_e32 v59, 0x6800, v58
	v_add_f32_e32 v136, v42, v136
	v_cvt_pk_bf16_f32 v46, v50, v51
	v_cvt_pk_bf16_f32 v47, v52, v53
	v_cvt_pk_bf16_f32 v48, v54, v55
	v_cvt_pk_bf16_f32 v42, v40, v41
	v_cvt_pk_bf16_f32 v41, v56, v57
	s_waitcnt lgkmcnt(0)
	v_mfma_f32_32x32x16_bf16 v[18:33], v[200:203], v[46:49], v[18:33]
	v_cvt_pk_bf16_f32 v43, v60, v61
	v_cvt_pk_bf16_f32 v44, v44, v45
	v_cvt_pk_bf16_f32 v45, v64, v65
	v_cvt_pk_bf16_f32 v39, v36, v37
	v_cvt_pk_bf16_f32 v40, v138, v139
	v_cvt_pk_bf16_f32 v35, v140, v141
	v_cvt_pk_bf16_f32 v36, v62, v63
	v_cvt_pk_bf16_f32 v37, v142, v143
	v_mfma_f32_32x32x16_bf16 v[2:17], v[216:219], v[46:49], v[2:17]
	v_mfma_f32_32x32x16_bf16 v[18:33], v[204:207], v[42:45], v[18:33]
	v_mfma_f32_32x32x16_bf16 v[2:17], v[220:223], v[42:45], v[2:17]
	v_mfma_f32_32x32x16_bf16 v[18:33], v[208:211], v[38:41], v[18:33]
	v_mfma_f32_32x32x16_bf16 v[2:17], v[224:227], v[38:41], v[2:17]
	v_mfma_f32_32x32x16_bf16 v[18:33], v[212:215], v[34:37], v[18:33]
	v_mfma_f32_32x32x16_bf16 v[2:17], v[228:231], v[34:37], v[2:17]
